# v76 + grid barrier: non-leader workgroups poll the cross-XCD generation word directly instead of the per-XCD release word (one release hop less)
# speedup vs baseline: 1.0054x; 1.0054x over previous
; __device__ __forceinline__ unsigned xb_ld(unsigned* p)              { return __hip_atomic_load(p, __ATOMIC_RELAXED, __HIP_MEMORY_SCOPE_AGENT); }
; __device__ __forceinline__ unsigned xb_add(unsigned* p, unsigned v) { return __hip_atomic_fetch_add(p, v, __ATOMIC_RELAXED, __HIP_MEMORY_SCOPE_AGENT); }
; #define XB_SPIN(cond, bar) do { unsigned _sp = 0; while (cond) { __builtin_amdgcn_s_sleep(1); \
;     if ((++_sp & 255u) == 0u) { if (xb_ld(&(bar)[XB_TMO])) break; if (_sp > XB_SPIN_CAP) { atomicAdd(&(bar)[XB_TMO], 1u); break; } } } } while (0)
; __device__ __forceinline__ void xcd_barrier(const XcdBarrier& b) {
;     ...
;         const unsigned old = xb_add(&bar[XB_XSUB(b.x)], 1u);
;         const unsigned gen = old / nloc;
;         if (old + 1u == (gen + 1u) * nloc) {
;     ...
;         } else {
;             XB_SPIN(xb_ld(&bar[XB_XGEN(b.x)]) == gen, bar);
.LBB0_32:
	v_readlane_b32 s2, v253, 35
	v_readlane_b32 s4, v253, 36
	s_lshl_b32 s2, s2, 6
	v_readlane_b32 s5, v253, 37
	s_mov_b32 s3, s4
	s_lshl_b64 s[2:3], s[2:3], 2
	v_readlane_b32 s4, v252, 15
	v_readlane_b32 s5, v252, 16
	s_add_u32 s2, s4, s2
	s_addc_u32 s3, s5, s3
	v_mov_b32_e32 v1, 0x1000
	global_atomic_add v3, v1, v232, s[2:3] offset:1024 sc0
	v_cvt_f32_u32_e32 v1, v2
	v_sub_u32_e32 v4, 0, v2
	v_rcp_iflag_f32_e32 v1, v1
	s_nop 0
	v_mul_f32_e32 v1, 0x4f7ffffe, v1
	v_cvt_u32_f32_e32 v1, v1
	v_mul_lo_u32 v4, v4, v1
	v_mul_hi_u32 v4, v1, v4
	v_add_u32_e32 v1, v1, v4
	s_waitcnt vmcnt(0)
	v_mul_hi_u32 v1, v3, v1
	v_mul_lo_u32 v4, v1, v2
	v_sub_u32_e32 v4, v3, v4
	v_add_u32_e32 v5, 1, v1
	v_cmp_ge_u32_e32 vcc, v4, v2
	v_add_u32_e32 v3, 1, v3
	s_nop 0
	v_cndmask_b32_e32 v1, v1, v5, vcc
	v_sub_u32_e32 v5, v4, v2
	v_cndmask_b32_e32 v4, v4, v5, vcc
	v_add_u32_e32 v5, 1, v1
	v_cmp_ge_u32_e32 vcc, v4, v2
	s_nop 1
	v_cndmask_b32_e32 v1, v1, v5, vcc
	v_mul_lo_u32 v4, v2, v1
	v_add_u32_e32 v2, v4, v2
	v_cmp_ne_u32_e32 vcc, v3, v2
	s_and_saveexec_b64 s[4:5], vcc
	s_xor_b64 s[4:5], exec, s[4:5]
	s_cbranch_execz .LBB0_46
	s_waitcnt lgkmcnt(0)
	v_readlane_b32 s8, v252, 15
	v_readlane_b32 s9, v252, 16
	s_nop 0
	s_add_u32 s8, s8, 0x3500
	s_addc_u32 s9, s9, 0
	global_load_dword v0, v195, s[8:9] sc1
	s_waitcnt vmcnt(0)
	v_cmp_eq_u32_e32 vcc, v0, v1
	s_and_saveexec_b64 s[6:7], vcc
	s_cbranch_execz .LBB0_45
	s_mov_b32 s20, 1
	s_mov_b64 s[10:11], 0
	s_branch .LBB0_36
